# stage_rstd (P1/P3a/P5 phase start): the 16 row-sum partial loads issued together instead of one load per vmcnt(0)
# speedup vs baseline: 1.0204x; 1.0108x over previous
.LBB0_149:
	s_ashr_i32 s6, s9, 3
	s_add_i32 s6, s12, s6
	s_ashr_i32 s7, s6, 31
	s_lshr_b32 s7, s7, 25
	s_add_i32 s7, s6, s7
	s_ashr_i32 s9, s7, 7
	s_lshl_b32 s9, s9, 3
	s_sub_i32 s11, 0x80, s9
	s_min_i32 s11, s11, 8
	s_abs_i32 s11, s11
	s_waitcnt lgkmcnt(0)
	v_cvt_f32_u32_e32 v3, s11
	s_sub_i32 s12, 0, s11
	s_and_b32 s7, s7, 0xffffff80
	s_sub_i32 s6, s6, s7
	v_rcp_iflag_f32_e32 v3, v3
	s_ashr_i32 s7, s6, 31
	s_abs_i32 s6, s6
	v_mul_f32_e32 v3, 0x4f7ffffe, v3
	v_cvt_u32_f32_e32 v3, v3
	s_nop 0
	v_readfirstlane_b32 s13, v3
	s_mul_i32 s12, s12, s13
	s_mul_hi_u32 s12, s13, s12
	s_add_i32 s13, s13, s12
	s_mul_hi_u32 s12, s6, s13
	s_mul_i32 s12, s12, s11
	s_sub_i32 s6, s6, s12
	s_sub_i32 s12, s6, s11
	s_cmp_ge_u32 s6, s11
	s_cselect_b32 s6, s12, s6
	s_sub_i32 s12, s6, s11
	s_cmp_ge_u32 s6, s11
	s_cselect_b32 s6, s12, s6
	s_xor_b32 s6, s6, s7
	s_sub_i32 s6, s6, s7
	s_add_i32 s11, s9, s6
	s_cmp_lg_u32 s11, s8
	s_cbranch_scc0 .LBB0_155
	s_and_saveexec_b64 s[8:9], s[4:5]
	s_cbranch_execz .LBB0_152
	v_lshl_add_u32 v4, s11, 8, v0
	v_lshlrev_b32_e32 v4, 2, v4
	global_load_dword v3, v4, s[28:29]
	s_add_u32 s76, s28, 0x20000
	s_addc_u32 s77, s29, 0
	global_load_dword v6, v4, s[76:77]
	s_add_u32 s76, s28, 0x40000
	s_addc_u32 s77, s29, 0
	global_load_dword v7, v4, s[76:77]
	s_add_u32 s76, s28, 0x60000
	s_addc_u32 s77, s29, 0
	global_load_dword v8, v4, s[76:77]
	s_add_u32 s76, s28, 0x80000
	s_addc_u32 s77, s29, 0
	global_load_dword v9, v4, s[76:77]
	s_add_u32 s76, s28, 0xa0000
	s_addc_u32 s77, s29, 0
	global_load_dword v10, v4, s[76:77]
	s_add_u32 s76, s28, 0xc0000
	s_addc_u32 s77, s29, 0
	global_load_dword v11, v4, s[76:77]
	s_add_u32 s76, s28, 0xe0000
	s_addc_u32 s77, s29, 0
	global_load_dword v12, v4, s[76:77]
	s_add_u32 s76, s28, 0x100000
	s_addc_u32 s77, s29, 0
	global_load_dword v13, v4, s[76:77]
	s_add_u32 s76, s28, 0x120000
	s_addc_u32 s77, s29, 0
	global_load_dword v14, v4, s[76:77]
	s_add_u32 s76, s28, 0x140000
	s_addc_u32 s77, s29, 0
	global_load_dword v15, v4, s[76:77]
	s_add_u32 s76, s28, 0x160000
	s_addc_u32 s77, s29, 0
	global_load_dword v16, v4, s[76:77]
	s_add_u32 s76, s28, 0x180000
	s_addc_u32 s77, s29, 0
	global_load_dword v17, v4, s[76:77]
	s_add_u32 s76, s28, 0x1a0000
	s_addc_u32 s77, s29, 0
	global_load_dword v18, v4, s[76:77]
	s_add_u32 s76, s28, 0x1c0000
	s_addc_u32 s77, s29, 0
	global_load_dword v19, v4, s[76:77]
	s_add_u32 s76, s28, 0x1e0000
	s_addc_u32 s77, s29, 0
	global_load_dword v20, v4, s[76:77]
	s_waitcnt vmcnt(0)
	v_add_f32_e32 v3, 0, v3
	v_add_f32_e32 v3, v3, v6
	v_add_f32_e32 v3, v3, v7
	v_add_f32_e32 v3, v3, v8
	v_add_f32_e32 v3, v3, v9
	v_add_f32_e32 v3, v3, v10
	v_add_f32_e32 v3, v3, v11
	v_add_f32_e32 v3, v3, v12
	v_add_f32_e32 v3, v3, v13
	v_add_f32_e32 v3, v3, v14
	v_add_f32_e32 v3, v3, v15
	v_add_f32_e32 v3, v3, v16
	v_add_f32_e32 v3, v3, v17
	v_add_f32_e32 v3, v3, v18
	v_add_f32_e32 v3, v3, v19
	v_add_f32_e32 v3, v3, v20
	v_fmamk_f32 v3, v3, 0x3a800000, v198
	v_mul_f32_e32 v4, 0x4f800000, v3
	v_cmp_gt_f32_e32 vcc, s96, v3
	s_nop 1
	v_cndmask_b32_e32 v3, v3, v4, vcc
	v_sqrt_f32_e32 v4, v3
	s_nop 0
	v_add_u32_e32 v5, -1, v4
	v_fma_f32 v6, -v5, v4, v3
	v_cmp_ge_f32_e64 s[6:7], 0, v6
	v_add_u32_e32 v6, 1, v4
	s_nop 0
	v_cndmask_b32_e64 v5, v4, v5, s[6:7]
	v_fma_f32 v4, -v6, v4, v3
	v_cmp_lt_f32_e64 s[6:7], 0, v4
	s_nop 1
	v_cndmask_b32_e64 v4, v5, v6, s[6:7]
	v_mul_f32_e32 v5, 0x37800000, v4
	v_cndmask_b32_e32 v4, v4, v5, vcc
	v_cmp_class_f32_e32 vcc, v3, v199
	s_nop 1
	v_cndmask_b32_e32 v3, v4, v3, vcc
	v_div_scale_f32 v4, s[6:7], v3, v3, 1.0
	v_rcp_f32_e32 v5, v4
	s_nop 0
	v_fma_f32 v6, -v4, v5, 1.0
	v_fmac_f32_e32 v5, v6, v5
	v_div_scale_f32 v6, vcc, 1.0, v3, 1.0
	v_mul_f32_e32 v7, v6, v5
	v_fma_f32 v8, -v4, v7, v6
	v_fmac_f32_e32 v7, v8, v5
	v_fma_f32 v4, -v4, v7, v6
	v_div_fmas_f32 v4, v4, v5, v7
	v_div_fixup_f32 v3, v4, v3, 1.0
	v_lshl_add_u32 v4, s10, 10, v2
	ds_write_b32 v4, v3

.LBB0_503:
	s_ashr_i32 s0, s43, 3
	s_add_i32 s0, s46, s0
	s_ashr_i32 s1, s0, 31
	s_lshr_b32 s1, s1, 25
	s_add_i32 s1, s0, s1
	s_ashr_i32 s43, s1, 7
	s_lshl_b32 s43, s43, 3
	s_sub_i32 s45, 64, s43
	s_min_i32 s45, s45, 8
	s_abs_i32 s45, s45
	v_cvt_f32_u32_e32 v3, s45
	s_sub_i32 s46, 0, s45
	s_and_b32 s1, s1, 0xffffff80
	s_sub_i32 s0, s0, s1
	v_rcp_iflag_f32_e32 v3, v3
	s_ashr_i32 s1, s0, 31
	s_abs_i32 s0, s0
	v_mul_f32_e32 v3, 0x4f7ffffe, v3
	v_cvt_u32_f32_e32 v3, v3
	s_nop 0
	v_readfirstlane_b32 s47, v3
	s_mul_i32 s46, s46, s47
	s_mul_hi_u32 s46, s47, s46
	s_add_i32 s47, s47, s46
	s_mul_hi_u32 s46, s0, s47
	s_mul_i32 s46, s46, s45
	s_sub_i32 s0, s0, s46
	s_sub_i32 s46, s0, s45
	s_cmp_ge_u32 s0, s45
	s_cselect_b32 s0, s46, s0
	s_sub_i32 s46, s0, s45
	s_cmp_ge_u32 s0, s45
	s_cselect_b32 s0, s46, s0
	s_xor_b32 s0, s0, s1
	s_sub_i32 s0, s0, s1
	s_add_i32 s0, s0, s67
	s_add_i32 s45, s0, s43
	s_cmp_lg_u32 s45, s42
	s_cbranch_scc0 .LBB0_509
	s_and_saveexec_b64 s[42:43], s[4:5]
	s_cbranch_execz .LBB0_506
	v_lshl_add_u32 v4, s45, 8, v0
	v_lshlrev_b32_e32 v4, 2, v4
	global_load_dword v3, v4, s[28:29]
	s_add_u32 s76, s28, 0x20000
	s_addc_u32 s77, s29, 0
	global_load_dword v6, v4, s[76:77]
	s_add_u32 s76, s28, 0x40000
	s_addc_u32 s77, s29, 0
	global_load_dword v7, v4, s[76:77]
	s_add_u32 s76, s28, 0x60000
	s_addc_u32 s77, s29, 0
	global_load_dword v8, v4, s[76:77]
	s_add_u32 s76, s28, 0x80000
	s_addc_u32 s77, s29, 0
	global_load_dword v9, v4, s[76:77]
	s_add_u32 s76, s28, 0xa0000
	s_addc_u32 s77, s29, 0
	global_load_dword v10, v4, s[76:77]
	s_add_u32 s76, s28, 0xc0000
	s_addc_u32 s77, s29, 0
	global_load_dword v11, v4, s[76:77]
	s_add_u32 s76, s28, 0xe0000
	s_addc_u32 s77, s29, 0
	global_load_dword v12, v4, s[76:77]
	s_add_u32 s76, s28, 0x100000
	s_addc_u32 s77, s29, 0
	global_load_dword v13, v4, s[76:77]
	s_add_u32 s76, s28, 0x120000
	s_addc_u32 s77, s29, 0
	global_load_dword v14, v4, s[76:77]
	s_add_u32 s76, s28, 0x140000
	s_addc_u32 s77, s29, 0
	global_load_dword v15, v4, s[76:77]
	s_add_u32 s76, s28, 0x160000
	s_addc_u32 s77, s29, 0
	global_load_dword v16, v4, s[76:77]
	s_add_u32 s76, s28, 0x180000
	s_addc_u32 s77, s29, 0
	global_load_dword v17, v4, s[76:77]
	s_add_u32 s76, s28, 0x1a0000
	s_addc_u32 s77, s29, 0
	global_load_dword v18, v4, s[76:77]
	s_add_u32 s76, s28, 0x1c0000
	s_addc_u32 s77, s29, 0
	global_load_dword v19, v4, s[76:77]
	s_add_u32 s76, s28, 0x1e0000
	s_addc_u32 s77, s29, 0
	global_load_dword v20, v4, s[76:77]
	s_waitcnt vmcnt(0)
	v_add_f32_e32 v3, 0, v3
	v_add_f32_e32 v3, v3, v6
	v_add_f32_e32 v3, v3, v7
	v_add_f32_e32 v3, v3, v8
	v_add_f32_e32 v3, v3, v9
	v_add_f32_e32 v3, v3, v10
	v_add_f32_e32 v3, v3, v11
	v_add_f32_e32 v3, v3, v12
	v_add_f32_e32 v3, v3, v13
	v_add_f32_e32 v3, v3, v14
	v_add_f32_e32 v3, v3, v15
	v_add_f32_e32 v3, v3, v16
	v_add_f32_e32 v3, v3, v17
	v_add_f32_e32 v3, v3, v18
	v_add_f32_e32 v3, v3, v19
	v_add_f32_e32 v3, v3, v20
	v_fmamk_f32 v3, v3, 0x3a800000, v198
	v_cmp_gt_f32_e32 vcc, s51, v3
	v_mul_f32_e32 v4, 0x4f800000, v3
	s_nop 0
	v_cndmask_b32_e32 v3, v3, v4, vcc
	v_sqrt_f32_e32 v4, v3
	s_nop 0
	v_add_u32_e32 v5, -1, v4
	v_fma_f32 v6, -v5, v4, v3
	v_cmp_ge_f32_e64 s[0:1], 0, v6
	v_add_u32_e32 v6, 1, v4
	s_nop 0
	v_cndmask_b32_e64 v5, v4, v5, s[0:1]
	v_fma_f32 v4, -v6, v4, v3
	v_cmp_lt_f32_e64 s[0:1], 0, v4
	s_nop 1
	v_cndmask_b32_e64 v4, v5, v6, s[0:1]
	v_mul_f32_e32 v5, 0x37800000, v4
	v_cndmask_b32_e32 v4, v4, v5, vcc
	v_cmp_class_f32_e32 vcc, v3, v199
	s_nop 1
	v_cndmask_b32_e32 v3, v4, v3, vcc
	v_div_scale_f32 v4, s[0:1], v3, v3, 1.0
	v_rcp_f32_e32 v5, v4
	s_nop 0
	v_fma_f32 v6, -v4, v5, 1.0
	v_fmac_f32_e32 v5, v6, v5
	v_div_scale_f32 v6, vcc, 1.0, v3, 1.0
	v_mul_f32_e32 v7, v6, v5
	v_fma_f32 v8, -v4, v7, v6
	v_fmac_f32_e32 v7, v8, v5
	v_fma_f32 v4, -v4, v7, v6
	v_div_fmas_f32 v4, v4, v5, v7
	v_div_fixup_f32 v3, v4, v3, 1.0
	v_lshl_add_u32 v4, s44, 10, v2
	ds_write_b32 v4, v3

.LBB0_937:
	s_ashr_i32 s0, s13, 3
	s_add_i32 s0, s42, s0
	s_ashr_i32 s1, s0, 31
	s_lshr_b32 s1, s1, 27
	s_add_i32 s1, s0, s1
	s_ashr_i32 s13, s1, 5
	s_lshl_b32 s13, s13, 3
	s_sub_i32 s41, 0x80, s13
	s_min_i32 s41, s41, 8
	s_abs_i32 s41, s41
	v_cvt_f32_u32_e32 v3, s41
	s_sub_i32 s42, 0, s41
	s_andn2_b32 s1, s1, 31
	s_sub_i32 s0, s0, s1
	v_rcp_iflag_f32_e32 v3, v3
	s_ashr_i32 s1, s0, 31
	s_abs_i32 s0, s0
	v_mul_f32_e32 v3, 0x4f7ffffe, v3
	v_cvt_u32_f32_e32 v3, v3
	s_nop 0
	v_readfirstlane_b32 s43, v3
	s_mul_i32 s42, s42, s43
	s_mul_hi_u32 s42, s43, s42
	s_add_i32 s43, s43, s42
	s_mul_hi_u32 s42, s0, s43
	s_mul_i32 s42, s42, s41
	s_sub_i32 s0, s0, s42
	s_sub_i32 s42, s0, s41
	s_cmp_ge_u32 s0, s41
	s_cselect_b32 s0, s42, s0
	s_sub_i32 s42, s0, s41
	s_cmp_ge_u32 s0, s41
	s_cselect_b32 s0, s42, s0
	s_xor_b32 s0, s0, s1
	s_sub_i32 s0, s0, s1
	s_add_i32 s41, s13, s0
	s_cmp_lg_u32 s41, s12
	s_cbranch_scc0 .LBB0_943
	s_and_saveexec_b64 s[12:13], s[4:5]
	s_cbranch_execz .LBB0_940
	v_lshl_add_u32 v4, s41, 8, v0
	v_lshl_add_u32 v4, s41, 8, v0
	v_readlane_b32 s0, v251, 55
	v_readlane_b32 s1, v251, 56
	s_nop 3
	v_lshlrev_b32_e32 v4, 2, v4
	global_load_dword v3, v4, s[0:1]
	s_add_u32 s76, s0, 0x20000
	s_addc_u32 s77, s1, 0
	global_load_dword v6, v4, s[76:77]
	s_add_u32 s76, s0, 0x40000
	s_addc_u32 s77, s1, 0
	global_load_dword v7, v4, s[76:77]
	s_add_u32 s76, s0, 0x60000
	s_addc_u32 s77, s1, 0
	global_load_dword v8, v4, s[76:77]
	s_add_u32 s76, s0, 0x80000
	s_addc_u32 s77, s1, 0
	global_load_dword v9, v4, s[76:77]
	s_add_u32 s76, s0, 0xa0000
	s_addc_u32 s77, s1, 0
	global_load_dword v10, v4, s[76:77]
	s_add_u32 s76, s0, 0xc0000
	s_addc_u32 s77, s1, 0
	global_load_dword v11, v4, s[76:77]
	s_add_u32 s76, s0, 0xe0000
	s_addc_u32 s77, s1, 0
	global_load_dword v12, v4, s[76:77]
	s_add_u32 s76, s0, 0x100000
	s_addc_u32 s77, s1, 0
	global_load_dword v13, v4, s[76:77]
	s_add_u32 s76, s0, 0x120000
	s_addc_u32 s77, s1, 0
	global_load_dword v14, v4, s[76:77]
	s_add_u32 s76, s0, 0x140000
	s_addc_u32 s77, s1, 0
	global_load_dword v15, v4, s[76:77]
	s_add_u32 s76, s0, 0x160000
	s_addc_u32 s77, s1, 0
	global_load_dword v16, v4, s[76:77]
	s_add_u32 s76, s0, 0x180000
	s_addc_u32 s77, s1, 0
	global_load_dword v17, v4, s[76:77]
	s_add_u32 s76, s0, 0x1a0000
	s_addc_u32 s77, s1, 0
	global_load_dword v18, v4, s[76:77]
	s_add_u32 s76, s0, 0x1c0000
	s_addc_u32 s77, s1, 0
	global_load_dword v19, v4, s[76:77]
	s_add_u32 s76, s0, 0x1e0000
	s_addc_u32 s77, s1, 0
	global_load_dword v20, v4, s[76:77]
	s_waitcnt vmcnt(0)
	v_add_f32_e32 v3, 0, v3
	v_add_f32_e32 v3, v3, v6
	v_add_f32_e32 v3, v3, v7
	v_add_f32_e32 v3, v3, v8
	v_add_f32_e32 v3, v3, v9
	v_add_f32_e32 v3, v3, v10
	v_add_f32_e32 v3, v3, v11
	v_add_f32_e32 v3, v3, v12
	v_add_f32_e32 v3, v3, v13
	v_add_f32_e32 v3, v3, v14
	v_add_f32_e32 v3, v3, v15
	v_add_f32_e32 v3, v3, v16
	v_add_f32_e32 v3, v3, v17
	v_add_f32_e32 v3, v3, v18
	v_add_f32_e32 v3, v3, v19
	v_add_f32_e32 v3, v3, v20
	v_fmamk_f32 v3, v3, 0x3a800000, v198
	v_cmp_gt_f32_e32 vcc, s96, v3
	v_mul_f32_e32 v4, 0x4f800000, v3
	s_nop 0
	v_cndmask_b32_e32 v3, v3, v4, vcc
	v_sqrt_f32_e32 v4, v3
	s_nop 0
	v_add_u32_e32 v5, -1, v4
	v_fma_f32 v6, -v5, v4, v3
	v_cmp_ge_f32_e64 s[0:1], 0, v6
	v_add_u32_e32 v6, 1, v4
	s_nop 0
	v_cndmask_b32_e64 v5, v4, v5, s[0:1]
	v_fma_f32 v4, -v6, v4, v3
	v_cmp_lt_f32_e64 s[0:1], 0, v4
	s_nop 1
	v_cndmask_b32_e64 v4, v5, v6, s[0:1]
	v_mul_f32_e32 v5, 0x37800000, v4
	v_cndmask_b32_e32 v4, v4, v5, vcc
	v_cmp_class_f32_e32 vcc, v3, v199
	s_nop 1
	v_cndmask_b32_e32 v3, v4, v3, vcc
	v_div_scale_f32 v4, s[0:1], v3, v3, 1.0
	v_rcp_f32_e32 v5, v4
	s_nop 0
	v_fma_f32 v6, -v4, v5, 1.0
	v_fmac_f32_e32 v5, v6, v5
	v_div_scale_f32 v6, vcc, 1.0, v3, 1.0
	v_mul_f32_e32 v7, v6, v5
	v_fma_f32 v8, -v4, v7, v6
	v_fmac_f32_e32 v7, v8, v5
	v_fma_f32 v4, -v4, v7, v6
	v_div_fmas_f32 v4, v4, v5, v7
	v_div_fixup_f32 v3, v4, v3, 1.0
	v_lshl_add_u32 v4, s40, 10, v2
	ds_write_b32 v4, v3
